# combo11 + P0 weight loop: wait for the prefetched item only at the register hand-over (real overlap of next item's loads with current item's transpose/stores)
# speedup vs baseline: 1.0015x; 1.0015x over previous
.LBB0_153:
	v_lshlrev_b32_e32 v2, 3, v0
	s_lshl_b32 s0, s93, 14
	v_and_b32_e32 v56, 56, v2
	v_lshrrev_b32_e32 v92, 3, v176
	s_add_i32 s0, s0, 0
	v_lshrrev_b32_e32 v90, 5, v176
	v_and_b32_e32 v91, 31, v0
	v_mov_b32_e32 v3, 0
	v_mul_u32_u24_e32 v2, 0x84, v56
	v_lshlrev_b32_e32 v4, 2, v92
	v_add3_u32 v93, s0, v2, v4
	v_lshl_add_u32 v34, v91, 2, s0
	v_mul_u32_u24_e32 v35, 0x84, v90
	v_mov_b32_e32 v4, v3
	v_mov_b32_e32 v5, v3
	v_mov_b32_e32 v6, v3
	v_mov_b32_e32 v7, v3
	v_mov_b32_e32 v8, v3
	v_mov_b32_e32 v9, v3
	v_mov_b32_e32 v10, v3
	v_mov_b32_e32 v11, v3
	v_mov_b32_e32 v12, v3
	v_mov_b32_e32 v13, v3
	v_mov_b32_e32 v14, v3
	v_mov_b32_e32 v15, v3
	v_mov_b32_e32 v16, v3
	v_mov_b32_e32 v17, v3
	v_mov_b32_e32 v18, v3
	v_mov_b32_e32 v19, v3
	v_mov_b32_e32 v20, v3
	v_mov_b32_e32 v21, v3
	v_mov_b32_e32 v22, v3
	v_mov_b32_e32 v23, v3
	v_mov_b32_e32 v24, v3
	v_mov_b32_e32 v25, v3
	v_mov_b32_e32 v26, v3
	v_mov_b32_e32 v27, v3
	v_mov_b32_e32 v28, v3
	v_mov_b32_e32 v29, v3
	v_mov_b32_e32 v30, v3
	v_mov_b32_e32 v31, v3
	v_mov_b32_e32 v32, v3
	v_mov_b32_e32 v33, v3
	v_mov_b32_e32 v2, v3
	v_add_u32_e32 v97, v34, v35
	v_mov_b64_e32 v[34:35], v[32:33]
	s_mov_b32 s2, 0
	s_lshl_b32 s28, s3, 3
	v_or_b32_e32 v94, 8, v92
	v_or_b32_e32 v95, 16, v92
	v_or_b32_e32 v96, 24, v92
	v_lshlrev_b32_e32 v58, 1, v56
	v_mov_b32_e32 v98, 0xfffffe00
	v_mov_b32_e32 v44, 1.0
	s_mov_b32 s29, s24
	v_mov_b64_e32 v[32:33], v[30:31]
	v_mov_b64_e32 v[30:31], v[28:29]
	v_mov_b64_e32 v[28:29], v[26:27]
	v_mov_b64_e32 v[26:27], v[24:25]
	v_mov_b64_e32 v[24:25], v[22:23]
	v_mov_b64_e32 v[22:23], v[20:21]
	v_mov_b64_e32 v[20:21], v[18:19]
	v_mov_b64_e32 v[18:19], v[16:17]
	v_mov_b64_e32 v[16:17], v[14:15]
	v_mov_b64_e32 v[14:15], v[12:13]
	v_mov_b64_e32 v[12:13], v[10:11]
	v_mov_b64_e32 v[10:11], v[8:9]
	v_mov_b64_e32 v[8:9], v[6:7]
	v_mov_b64_e32 v[6:7], v[4:5]
	v_mov_b64_e32 v[4:5], v[2:3]
	s_waitcnt vmcnt(0)
	s_branch .LBB0_155

.LBB0_288:
	s_abs_i32 s12, s27
	v_cvt_f32_u32_e32 v2, s12
	s_sub_i32 s15, 0, s12
	v_add_u32_e32 v45, 0x400, v97
	s_abs_i32 s14, s25
	v_rcp_iflag_f32_e32 v2, v2
	ds_write2_b32 v97, v1, v57 offset1:66
	ds_write2_b32 v97, v61, v60 offset0:132 offset1:198
	ds_write2_b32 v45, v63, v62 offset0:8 offset1:74
	ds_write2_b32 v45, v65, v64 offset0:140 offset1:206
	s_xor_b32 s13, s25, s27
	v_mul_f32_e32 v2, 0x4f7ffffe, v2
	v_cvt_u32_f32_e32 v2, v2
	s_ashr_i32 s13, s13, 31
	v_mov_b32_e32 v59, v3
	v_readfirstlane_b32 s16, v2
	s_mul_i32 s15, s15, s16
	s_mul_hi_u32 s15, s16, s15
	v_add_u32_e32 v2, 0x800, v97
	s_add_i32 s16, s16, s15
	ds_write2_b32 v2, v67, v66 offset0:16 offset1:82
	ds_write2_b32 v2, v69, v68 offset0:148 offset1:214
	v_add_u32_e32 v2, 0xc00, v97
	s_mul_hi_u32 s15, s14, s16
	ds_write2_b32 v2, v71, v70 offset0:24 offset1:90
	ds_write2_b32 v2, v73, v72 offset0:156 offset1:222
	v_add_u32_e32 v2, 0x1000, v97
	s_mul_i32 s16, s15, s12
	ds_write2_b32 v2, v75, v74 offset0:32 offset1:98
	ds_write2_b32 v2, v77, v76 offset0:164 offset1:230
	v_add_u32_e32 v2, 0x1400, v97
	s_sub_i32 s14, s14, s16
	ds_write2_b32 v2, v79, v78 offset0:40 offset1:106
	ds_write2_b32 v2, v81, v80 offset0:172 offset1:238
	v_add_u32_e32 v2, 0x1800, v97
	s_add_i32 s17, s15, 1
	s_sub_i32 s16, s14, s12
	ds_write2_b32 v2, v83, v82 offset0:48 offset1:114
	ds_write2_b32 v2, v85, v84 offset0:180 offset1:246
	v_add_u32_e32 v2, 0x1c00, v97
	s_cmp_ge_u32 s14, s12
	ds_write2_b32 v2, v87, v86 offset0:56 offset1:122
	ds_write2_b32 v2, v89, v88 offset0:188 offset1:254
	s_cselect_b32 s15, s17, s15
	s_waitcnt lgkmcnt(0)
	s_cselect_b32 s14, s16, s14
	s_add_i32 s16, s15, 1
	ds_read2_b32 v[46:47], v93 offset1:8
	ds_read2_b32 v[104:105], v93 offset0:33 offset1:41
	ds_read2_b32 v[106:107], v93 offset0:66 offset1:74
	ds_read2_b32 v[108:109], v93 offset0:99 offset1:107
	s_cmp_ge_u32 s14, s12
	s_cselect_b32 s12, s16, s15
	ds_read2_b32 v[110:111], v93 offset0:132 offset1:140
	ds_read2_b32 v[112:113], v93 offset0:165 offset1:173
	ds_read2_b32 v[114:115], v93 offset0:198 offset1:206
	ds_read2_b32 v[116:117], v93 offset0:231 offset1:239
	s_xor_b32 s12, s12, s13
	s_sub_i32 s13, s12, s13
	s_lshl_b32 s12, s13, 6
	s_mul_i32 s13, s13, s27
	s_waitcnt lgkmcnt(7)
	v_mov_b32_e32 v100, v46
	s_waitcnt lgkmcnt(6)
	v_mov_b32_e32 v101, v104
	s_waitcnt lgkmcnt(5)
	v_mov_b32_e32 v102, v106
	s_waitcnt lgkmcnt(4)
	v_mov_b32_e32 v103, v108
	s_sub_i32 s13, s25, s13
	v_pk_mul_f32 v[100:101], v[36:37], v[100:101]
	v_pk_mul_f32 v[102:103], v[38:39], v[102:103]
	s_lshl_b32 s16, s13, 5
	v_cvt_pk_bf16_f32 v100, v100, v101
	v_cvt_pk_bf16_f32 v101, v102, v103
	s_waitcnt lgkmcnt(3)
	v_mov_b32_e32 v102, v110
	s_waitcnt lgkmcnt(2)
	v_mov_b32_e32 v103, v112
	s_waitcnt lgkmcnt(1)
	v_mov_b32_e32 v118, v114
	s_waitcnt lgkmcnt(0)
	v_mov_b32_e32 v119, v116
	v_pk_mul_f32 v[102:103], v[40:41], v[102:103]
	v_pk_mul_f32 v[118:119], v[42:43], v[118:119]
	v_or_b32_e32 v2, s16, v92
	s_ashr_i32 s13, s12, 31
	v_cvt_pk_bf16_f32 v102, v102, v103
	v_cvt_pk_bf16_f32 v103, v118, v119
	v_mad_i64_i32 v[118:119], s[14:15], v2, s26, 0
	v_lshl_add_u64 v[118:119], v[118:119], 1, s[6:7]
	s_lshl_b64 s[12:13], s[12:13], 1
	v_lshl_add_u64 v[118:119], v[118:119], 0, s[12:13]
	v_mov_b32_e32 v104, v47
	v_lshl_add_u64 v[118:119], v[118:119], 0, v[58:59]
	v_pk_mul_f32 v[46:47], v[36:37], v[104:105]
	v_mov_b32_e32 v108, v107
	global_store_dwordx4 v[118:119], v[100:103], off
	v_mov_b32_e32 v112, v111
	v_mov_b32_e32 v116, v115
	v_cvt_pk_bf16_f32 v100, v46, v47
	v_pk_mul_f32 v[46:47], v[38:39], v[108:109]
	v_or_b32_e32 v2, s16, v94
	v_cvt_pk_bf16_f32 v101, v46, v47
	v_pk_mul_f32 v[46:47], v[40:41], v[112:113]
	ds_read2_b32 v[104:105], v93 offset0:16 offset1:24
	v_cvt_pk_bf16_f32 v102, v46, v47
	v_pk_mul_f32 v[46:47], v[42:43], v[116:117]
	ds_read2_b32 v[106:107], v93 offset0:49 offset1:57
	v_cvt_pk_bf16_f32 v103, v46, v47
	v_mad_i64_i32 v[46:47], s[14:15], v2, s26, 0
	v_lshl_add_u64 v[46:47], v[46:47], 1, s[6:7]
	ds_read2_b32 v[108:109], v93 offset0:82 offset1:90
	ds_read2_b32 v[110:111], v93 offset0:115 offset1:123
	v_lshl_add_u64 v[46:47], v[46:47], 0, s[12:13]
	v_lshl_add_u64 v[46:47], v[46:47], 0, v[58:59]
	ds_read2_b32 v[112:113], v93 offset0:148 offset1:156
	ds_read2_b32 v[114:115], v93 offset0:181 offset1:189
	global_store_dwordx4 v[46:47], v[100:103], off
	s_waitcnt lgkmcnt(5)
	v_mov_b32_e32 v46, v104
	s_waitcnt lgkmcnt(4)
	v_mov_b32_e32 v47, v106
	v_pk_mul_f32 v[46:47], v[36:37], v[46:47]
	ds_read2_b32 v[116:117], v93 offset0:214 offset1:222
	ds_read2_b32 v[118:119], v93 offset0:247 offset1:255
	v_cvt_pk_bf16_f32 v100, v46, v47
	s_waitcnt lgkmcnt(5)
	v_mov_b32_e32 v46, v108
	s_waitcnt lgkmcnt(4)
	v_mov_b32_e32 v47, v110
	v_pk_mul_f32 v[46:47], v[38:39], v[46:47]
	v_or_b32_e32 v2, s16, v95
	v_cvt_pk_bf16_f32 v101, v46, v47
	s_waitcnt lgkmcnt(3)
	v_mov_b32_e32 v46, v112
	s_waitcnt lgkmcnt(2)
	v_mov_b32_e32 v47, v114
	v_pk_mul_f32 v[46:47], v[40:41], v[46:47]
	v_mov_b32_e32 v106, v105
	v_cvt_pk_bf16_f32 v102, v46, v47
	s_waitcnt lgkmcnt(1)
	v_mov_b32_e32 v46, v116
	s_waitcnt lgkmcnt(0)
	v_mov_b32_e32 v47, v118
	v_pk_mul_f32 v[46:47], v[42:43], v[46:47]
	v_mov_b32_e32 v110, v109
	v_cvt_pk_bf16_f32 v103, v46, v47
	v_mad_i64_i32 v[46:47], s[14:15], v2, s26, 0
	v_lshl_add_u64 v[46:47], v[46:47], 1, s[6:7]
	v_lshl_add_u64 v[46:47], v[46:47], 0, s[12:13]
	v_lshl_add_u64 v[46:47], v[46:47], 0, v[58:59]
	global_store_dwordx4 v[46:47], v[100:103], off
	v_pk_mul_f32 v[46:47], v[36:37], v[106:107]
	v_mov_b32_e32 v114, v113
	v_cvt_pk_bf16_f32 v100, v46, v47
	v_pk_mul_f32 v[46:47], v[38:39], v[110:111]
	v_mov_b32_e32 v118, v117
	v_cvt_pk_bf16_f32 v101, v46, v47
	v_pk_mul_f32 v[46:47], v[40:41], v[114:115]
	v_or_b32_e32 v2, s16, v96
	v_cvt_pk_bf16_f32 v102, v46, v47
	v_pk_mul_f32 v[46:47], v[42:43], v[118:119]
	s_andn2_b64 vcc, exec, s[10:11]
	v_cvt_pk_bf16_f32 v103, v46, v47
	v_mad_i64_i32 v[46:47], s[14:15], v2, s26, 0
	v_lshl_add_u64 v[46:47], v[46:47], 1, s[6:7]
	v_lshl_add_u64 v[46:47], v[46:47], 0, s[12:13]
	v_lshl_add_u64 v[46:47], v[46:47], 0, v[58:59]
	global_store_dwordx4 v[46:47], v[100:103], off
	s_waitcnt lgkmcnt(0)
	s_cbranch_vccnz .LBB0_154
	s_waitcnt vmcnt(4)
	v_mov_b64_e32 v[40:41], v[52:53]
	v_mov_b64_e32 v[36:37], v[48:49]
	v_mov_b32_e32 v84, v31
	v_mov_b32_e32 v85, v30
	v_mov_b32_e32 v82, v29
	v_mov_b32_e32 v83, v28
	v_mov_b32_e32 v80, v27
	v_mov_b32_e32 v81, v26
	v_mov_b32_e32 v78, v25
	v_mov_b32_e32 v79, v24
	v_mov_b32_e32 v76, v23
	v_mov_b32_e32 v77, v22
	v_mov_b32_e32 v74, v21
	v_mov_b32_e32 v75, v20
	v_mov_b32_e32 v72, v19
	v_mov_b32_e32 v73, v18
	v_mov_b32_e32 v70, v17
	v_mov_b32_e32 v71, v16
	v_mov_b32_e32 v68, v15
	v_mov_b32_e32 v69, v14
	v_mov_b32_e32 v66, v13
	v_mov_b32_e32 v67, v12
	v_mov_b32_e32 v64, v11
	v_mov_b32_e32 v65, v10
	v_mov_b32_e32 v62, v9
	v_mov_b32_e32 v63, v8
	v_mov_b32_e32 v60, v7
	v_mov_b32_e32 v61, v6
	v_mov_b32_e32 v57, v5
	v_mov_b32_e32 v1, v4
	v_mov_b32_e32 v87, v32
	v_mov_b32_e32 v86, v33
	v_mov_b32_e32 v89, v34
	v_mov_b32_e32 v88, v35
	v_mov_b64_e32 v[42:43], v[54:55]
	v_mov_b64_e32 v[38:39], v[50:51]
	s_mov_b64 s[6:7], s[0:1]
	s_mov_b32 s25, s30
	s_mov_b32 s27, s33
	s_mov_b32 s26, s31
	s_branch .LBB0_154
